# P0 weight-transpose items: all 32 row loads and gains of an item in flight before the first wait (three serialized item loops rewritten)
# baseline (speedup 1.0000x reference)
.LBB0_24:
	v_mov_b32_e32 v208, v44
	v_mov_b32_e32 v209, v45
	v_mov_b32_e32 v212, 0x8000
	v_mov_b32_e32 v213, 0
	global_load_dword v112, v[208:209], off
	v_lshl_add_u64 v[208:209], v[208:209], 0, v[212:213]
	global_load_dword v113, v[208:209], off
	v_lshl_add_u64 v[208:209], v[208:209], 0, v[212:213]
	global_load_dword v114, v[208:209], off
	v_lshl_add_u64 v[208:209], v[208:209], 0, v[212:213]
	global_load_dword v115, v[208:209], off
	v_lshl_add_u64 v[208:209], v[208:209], 0, v[212:213]
	global_load_dword v116, v[208:209], off
	v_lshl_add_u64 v[208:209], v[208:209], 0, v[212:213]
	global_load_dword v117, v[208:209], off
	v_lshl_add_u64 v[208:209], v[208:209], 0, v[212:213]
	global_load_dword v118, v[208:209], off
	v_lshl_add_u64 v[208:209], v[208:209], 0, v[212:213]
	global_load_dword v119, v[208:209], off
	v_lshl_add_u64 v[208:209], v[208:209], 0, v[212:213]
	global_load_dword v120, v[208:209], off
	v_lshl_add_u64 v[208:209], v[208:209], 0, v[212:213]
	global_load_dword v121, v[208:209], off
	v_lshl_add_u64 v[208:209], v[208:209], 0, v[212:213]
	global_load_dword v122, v[208:209], off
	v_lshl_add_u64 v[208:209], v[208:209], 0, v[212:213]
	global_load_dword v123, v[208:209], off
	v_lshl_add_u64 v[208:209], v[208:209], 0, v[212:213]
	global_load_dword v124, v[208:209], off
	v_lshl_add_u64 v[208:209], v[208:209], 0, v[212:213]
	global_load_dword v125, v[208:209], off
	v_lshl_add_u64 v[208:209], v[208:209], 0, v[212:213]
	global_load_dword v126, v[208:209], off
	v_lshl_add_u64 v[208:209], v[208:209], 0, v[212:213]
	global_load_dword v127, v[208:209], off
	v_lshl_add_u64 v[208:209], v[208:209], 0, v[212:213]
	global_load_dword v128, v[208:209], off
	v_lshl_add_u64 v[208:209], v[208:209], 0, v[212:213]
	global_load_dword v129, v[208:209], off
	v_lshl_add_u64 v[208:209], v[208:209], 0, v[212:213]
	global_load_dword v130, v[208:209], off
	v_lshl_add_u64 v[208:209], v[208:209], 0, v[212:213]
	global_load_dword v131, v[208:209], off
	v_lshl_add_u64 v[208:209], v[208:209], 0, v[212:213]
	global_load_dword v132, v[208:209], off
	v_lshl_add_u64 v[208:209], v[208:209], 0, v[212:213]
	global_load_dword v133, v[208:209], off
	v_lshl_add_u64 v[208:209], v[208:209], 0, v[212:213]
	global_load_dword v134, v[208:209], off
	v_lshl_add_u64 v[208:209], v[208:209], 0, v[212:213]
	global_load_dword v135, v[208:209], off
	v_lshl_add_u64 v[208:209], v[208:209], 0, v[212:213]
	global_load_dword v136, v[208:209], off
	v_lshl_add_u64 v[208:209], v[208:209], 0, v[212:213]
	global_load_dword v137, v[208:209], off
	v_lshl_add_u64 v[208:209], v[208:209], 0, v[212:213]
	global_load_dword v138, v[208:209], off
	v_lshl_add_u64 v[208:209], v[208:209], 0, v[212:213]
	global_load_dword v139, v[208:209], off
	v_lshl_add_u64 v[208:209], v[208:209], 0, v[212:213]
	global_load_dword v140, v[208:209], off
	v_lshl_add_u64 v[208:209], v[208:209], 0, v[212:213]
	global_load_dword v141, v[208:209], off
	v_lshl_add_u64 v[208:209], v[208:209], 0, v[212:213]
	global_load_dword v142, v[208:209], off
	v_lshl_add_u64 v[208:209], v[208:209], 0, v[212:213]
	global_load_dword v143, v[208:209], off
	global_load_dword v176, v46, s[40:41]
	global_load_dword v177, v46, s[40:41] offset:8
	global_load_dword v178, v46, s[40:41] offset:16
	global_load_dword v179, v46, s[40:41] offset:24
	global_load_dword v180, v46, s[40:41] offset:32
	global_load_dword v181, v46, s[40:41] offset:40
	global_load_dword v182, v46, s[40:41] offset:48
	global_load_dword v183, v46, s[40:41] offset:56
	global_load_dword v184, v46, s[40:41] offset:64
	global_load_dword v185, v46, s[40:41] offset:72
	global_load_dword v186, v46, s[40:41] offset:80
	global_load_dword v187, v46, s[40:41] offset:88
	global_load_dword v188, v46, s[40:41] offset:96
	global_load_dword v189, v46, s[40:41] offset:104
	global_load_dword v190, v46, s[40:41] offset:112
	global_load_dword v191, v46, s[40:41] offset:120
	global_load_dword v192, v46, s[40:41] offset:128
	global_load_dword v193, v46, s[40:41] offset:136
	global_load_dword v194, v46, s[40:41] offset:144
	global_load_dword v195, v46, s[40:41] offset:152
	global_load_dword v196, v46, s[40:41] offset:160
	global_load_dword v197, v46, s[40:41] offset:168
	global_load_dword v198, v46, s[40:41] offset:176
	global_load_dword v199, v46, s[40:41] offset:184
	global_load_dword v200, v46, s[40:41] offset:192
	global_load_dword v201, v46, s[40:41] offset:200
	global_load_dword v202, v46, s[40:41] offset:208
	global_load_dword v203, v46, s[40:41] offset:216
	global_load_dword v204, v46, s[40:41] offset:224
	global_load_dword v205, v46, s[40:41] offset:232
	global_load_dword v206, v46, s[40:41] offset:240
	global_load_dword v207, v46, s[40:41] offset:248
	s_waitcnt vmcnt(0)
	v_mul_f32_e32 v112, v176, v112
	ds_write_b32 v4, v112
	v_mul_f32_e32 v113, v177, v113
	ds_write_b32 v4, v113 offset:264
	v_mul_f32_e32 v114, v178, v114
	ds_write_b32 v4, v114 offset:528
	v_mul_f32_e32 v115, v179, v115
	ds_write_b32 v4, v115 offset:792
	v_mul_f32_e32 v116, v180, v116
	ds_write_b32 v4, v116 offset:1056
	v_mul_f32_e32 v117, v181, v117
	ds_write_b32 v4, v117 offset:1320
	v_mul_f32_e32 v118, v182, v118
	ds_write_b32 v4, v118 offset:1584
	v_mul_f32_e32 v119, v183, v119
	ds_write_b32 v4, v119 offset:1848
	v_mul_f32_e32 v120, v184, v120
	ds_write_b32 v4, v120 offset:2112
	v_mul_f32_e32 v121, v185, v121
	ds_write_b32 v4, v121 offset:2376
	v_mul_f32_e32 v122, v186, v122
	ds_write_b32 v4, v122 offset:2640
	v_mul_f32_e32 v123, v187, v123
	ds_write_b32 v4, v123 offset:2904
	v_mul_f32_e32 v124, v188, v124
	ds_write_b32 v4, v124 offset:3168
	v_mul_f32_e32 v125, v189, v125
	ds_write_b32 v4, v125 offset:3432
	v_mul_f32_e32 v126, v190, v126
	ds_write_b32 v4, v126 offset:3696
	v_mul_f32_e32 v127, v191, v127
	ds_write_b32 v4, v127 offset:3960
	v_mul_f32_e32 v128, v192, v128
	ds_write_b32 v4, v128 offset:4224
	v_mul_f32_e32 v129, v193, v129
	ds_write_b32 v4, v129 offset:4488
	v_mul_f32_e32 v130, v194, v130
	ds_write_b32 v4, v130 offset:4752
	v_mul_f32_e32 v131, v195, v131
	ds_write_b32 v4, v131 offset:5016
	v_mul_f32_e32 v132, v196, v132
	ds_write_b32 v4, v132 offset:5280
	v_mul_f32_e32 v133, v197, v133
	ds_write_b32 v4, v133 offset:5544
	v_mul_f32_e32 v134, v198, v134
	ds_write_b32 v4, v134 offset:5808
	v_mul_f32_e32 v135, v199, v135
	ds_write_b32 v4, v135 offset:6072
	v_mul_f32_e32 v136, v200, v136
	ds_write_b32 v4, v136 offset:6336
	v_mul_f32_e32 v137, v201, v137
	ds_write_b32 v4, v137 offset:6600
	v_mul_f32_e32 v138, v202, v138
	ds_write_b32 v4, v138 offset:6864
	v_mul_f32_e32 v139, v203, v139
	ds_write_b32 v4, v139 offset:7128
	v_mul_f32_e32 v140, v204, v140
	ds_write_b32 v4, v140 offset:7392
	v_mul_f32_e32 v141, v205, v141
	ds_write_b32 v4, v141 offset:7656
	v_mul_f32_e32 v142, v206, v142
	ds_write_b32 v4, v142 offset:7920
	v_mul_f32_e32 v143, v207, v143
	ds_write_b32 v4, v143 offset:8184
	s_branch .LBB0_40

.LBB0_46:
	v_mov_b32_e32 v208, v34
	v_mov_b32_e32 v209, v35
	v_lshlrev_b32_e32 v210, 2, v4
	v_readfirstlane_b32 s98, v4
	v_mov_b32_e32 v212, 0x2000
	v_mov_b32_e32 v213, 0
	global_load_dword v112, v[208:209], off
	v_lshl_add_u64 v[208:209], v[208:209], 0, v[212:213]
	global_load_dword v113, v[208:209], off
	v_lshl_add_u64 v[208:209], v[208:209], 0, v[212:213]
	global_load_dword v114, v[208:209], off
	v_lshl_add_u64 v[208:209], v[208:209], 0, v[212:213]
	global_load_dword v115, v[208:209], off
	v_lshl_add_u64 v[208:209], v[208:209], 0, v[212:213]
	global_load_dword v116, v[208:209], off
	v_lshl_add_u64 v[208:209], v[208:209], 0, v[212:213]
	global_load_dword v117, v[208:209], off
	v_lshl_add_u64 v[208:209], v[208:209], 0, v[212:213]
	global_load_dword v118, v[208:209], off
	v_lshl_add_u64 v[208:209], v[208:209], 0, v[212:213]
	global_load_dword v119, v[208:209], off
	v_lshl_add_u64 v[208:209], v[208:209], 0, v[212:213]
	global_load_dword v120, v[208:209], off
	v_lshl_add_u64 v[208:209], v[208:209], 0, v[212:213]
	global_load_dword v121, v[208:209], off
	v_lshl_add_u64 v[208:209], v[208:209], 0, v[212:213]
	global_load_dword v122, v[208:209], off
	v_lshl_add_u64 v[208:209], v[208:209], 0, v[212:213]
	global_load_dword v123, v[208:209], off
	v_lshl_add_u64 v[208:209], v[208:209], 0, v[212:213]
	global_load_dword v124, v[208:209], off
	v_lshl_add_u64 v[208:209], v[208:209], 0, v[212:213]
	global_load_dword v125, v[208:209], off
	v_lshl_add_u64 v[208:209], v[208:209], 0, v[212:213]
	global_load_dword v126, v[208:209], off
	v_lshl_add_u64 v[208:209], v[208:209], 0, v[212:213]
	global_load_dword v127, v[208:209], off
	v_lshl_add_u64 v[208:209], v[208:209], 0, v[212:213]
	global_load_dword v128, v[208:209], off
	v_lshl_add_u64 v[208:209], v[208:209], 0, v[212:213]
	global_load_dword v129, v[208:209], off
	v_lshl_add_u64 v[208:209], v[208:209], 0, v[212:213]
	global_load_dword v130, v[208:209], off
	v_lshl_add_u64 v[208:209], v[208:209], 0, v[212:213]
	global_load_dword v131, v[208:209], off
	v_lshl_add_u64 v[208:209], v[208:209], 0, v[212:213]
	global_load_dword v132, v[208:209], off
	v_lshl_add_u64 v[208:209], v[208:209], 0, v[212:213]
	global_load_dword v133, v[208:209], off
	v_lshl_add_u64 v[208:209], v[208:209], 0, v[212:213]
	global_load_dword v134, v[208:209], off
	v_lshl_add_u64 v[208:209], v[208:209], 0, v[212:213]
	global_load_dword v135, v[208:209], off
	v_lshl_add_u64 v[208:209], v[208:209], 0, v[212:213]
	global_load_dword v136, v[208:209], off
	v_lshl_add_u64 v[208:209], v[208:209], 0, v[212:213]
	global_load_dword v137, v[208:209], off
	v_lshl_add_u64 v[208:209], v[208:209], 0, v[212:213]
	global_load_dword v138, v[208:209], off
	v_lshl_add_u64 v[208:209], v[208:209], 0, v[212:213]
	global_load_dword v139, v[208:209], off
	v_lshl_add_u64 v[208:209], v[208:209], 0, v[212:213]
	global_load_dword v140, v[208:209], off
	v_lshl_add_u64 v[208:209], v[208:209], 0, v[212:213]
	global_load_dword v141, v[208:209], off
	v_lshl_add_u64 v[208:209], v[208:209], 0, v[212:213]
	global_load_dword v142, v[208:209], off
	v_lshl_add_u64 v[208:209], v[208:209], 0, v[212:213]
	global_load_dword v143, v[208:209], off
	s_cmp_lt_u32 s98, 0x200
	s_cbranch_scc0 .Lp0_wout_sc2
	global_load_dword v176, v210, s[26:27]
	global_load_dword v177, v210, s[26:27] offset:8
	global_load_dword v178, v210, s[26:27] offset:16
	global_load_dword v179, v210, s[26:27] offset:24
	global_load_dword v180, v210, s[26:27] offset:32
	global_load_dword v181, v210, s[26:27] offset:40
	global_load_dword v182, v210, s[26:27] offset:48
	global_load_dword v183, v210, s[26:27] offset:56
	global_load_dword v184, v210, s[26:27] offset:64
	global_load_dword v185, v210, s[26:27] offset:72
	global_load_dword v186, v210, s[26:27] offset:80
	global_load_dword v187, v210, s[26:27] offset:88
	global_load_dword v188, v210, s[26:27] offset:96
	global_load_dword v189, v210, s[26:27] offset:104
	global_load_dword v190, v210, s[26:27] offset:112
	global_load_dword v191, v210, s[26:27] offset:120
	global_load_dword v192, v210, s[26:27] offset:128
	global_load_dword v193, v210, s[26:27] offset:136
	global_load_dword v194, v210, s[26:27] offset:144
	global_load_dword v195, v210, s[26:27] offset:152
	global_load_dword v196, v210, s[26:27] offset:160
	global_load_dword v197, v210, s[26:27] offset:168
	global_load_dword v198, v210, s[26:27] offset:176
	global_load_dword v199, v210, s[26:27] offset:184
	global_load_dword v200, v210, s[26:27] offset:192
	global_load_dword v201, v210, s[26:27] offset:200
	global_load_dword v202, v210, s[26:27] offset:208
	global_load_dword v203, v210, s[26:27] offset:216
	global_load_dword v204, v210, s[26:27] offset:224
	global_load_dword v205, v210, s[26:27] offset:232
	global_load_dword v206, v210, s[26:27] offset:240
	global_load_dword v207, v210, s[26:27] offset:248
	s_waitcnt vmcnt(0)
	v_mul_f32_e32 v176, 0x3f4ccccd, v176
	v_mul_f32_e32 v177, 0x3f4ccccd, v177
	v_mul_f32_e32 v178, 0x3f4ccccd, v178
	v_mul_f32_e32 v179, 0x3f4ccccd, v179
	v_mul_f32_e32 v180, 0x3f4ccccd, v180
	v_mul_f32_e32 v181, 0x3f4ccccd, v181
	v_mul_f32_e32 v182, 0x3f4ccccd, v182
	v_mul_f32_e32 v183, 0x3f4ccccd, v183
	v_mul_f32_e32 v184, 0x3f4ccccd, v184
	v_mul_f32_e32 v185, 0x3f4ccccd, v185
	v_mul_f32_e32 v186, 0x3f4ccccd, v186
	v_mul_f32_e32 v187, 0x3f4ccccd, v187
	v_mul_f32_e32 v188, 0x3f4ccccd, v188
	v_mul_f32_e32 v189, 0x3f4ccccd, v189
	v_mul_f32_e32 v190, 0x3f4ccccd, v190
	v_mul_f32_e32 v191, 0x3f4ccccd, v191
	v_mul_f32_e32 v192, 0x3f4ccccd, v192
	v_mul_f32_e32 v193, 0x3f4ccccd, v193
	v_mul_f32_e32 v194, 0x3f4ccccd, v194
	v_mul_f32_e32 v195, 0x3f4ccccd, v195
	v_mul_f32_e32 v196, 0x3f4ccccd, v196
	v_mul_f32_e32 v197, 0x3f4ccccd, v197
	v_mul_f32_e32 v198, 0x3f4ccccd, v198
	v_mul_f32_e32 v199, 0x3f4ccccd, v199
	v_mul_f32_e32 v200, 0x3f4ccccd, v200
	v_mul_f32_e32 v201, 0x3f4ccccd, v201
	v_mul_f32_e32 v202, 0x3f4ccccd, v202
	v_mul_f32_e32 v203, 0x3f4ccccd, v203
	v_mul_f32_e32 v204, 0x3f4ccccd, v204
	v_mul_f32_e32 v205, 0x3f4ccccd, v205
	v_mul_f32_e32 v206, 0x3f4ccccd, v206
	v_mul_f32_e32 v207, 0x3f4ccccd, v207
	s_branch .Lp0_wout_mul
.Lp0_wout_sc2:
	global_load_dword v176, v210, s[28:29] offset:-2048
	global_load_dword v177, v210, s[28:29] offset:-2040
	global_load_dword v178, v210, s[28:29] offset:-2032
	global_load_dword v179, v210, s[28:29] offset:-2024
	global_load_dword v180, v210, s[28:29] offset:-2016
	global_load_dword v181, v210, s[28:29] offset:-2008
	global_load_dword v182, v210, s[28:29] offset:-2000
	global_load_dword v183, v210, s[28:29] offset:-1992
	global_load_dword v184, v210, s[28:29] offset:-1984
	global_load_dword v185, v210, s[28:29] offset:-1976
	global_load_dword v186, v210, s[28:29] offset:-1968
	global_load_dword v187, v210, s[28:29] offset:-1960
	global_load_dword v188, v210, s[28:29] offset:-1952
	global_load_dword v189, v210, s[28:29] offset:-1944
	global_load_dword v190, v210, s[28:29] offset:-1936
	global_load_dword v191, v210, s[28:29] offset:-1928
	global_load_dword v192, v210, s[28:29] offset:-1920
	global_load_dword v193, v210, s[28:29] offset:-1912
	global_load_dword v194, v210, s[28:29] offset:-1904
	global_load_dword v195, v210, s[28:29] offset:-1896
	global_load_dword v196, v210, s[28:29] offset:-1888
	global_load_dword v197, v210, s[28:29] offset:-1880
	global_load_dword v198, v210, s[28:29] offset:-1872
	global_load_dword v199, v210, s[28:29] offset:-1864
	global_load_dword v200, v210, s[28:29] offset:-1856
	global_load_dword v201, v210, s[28:29] offset:-1848
	global_load_dword v202, v210, s[28:29] offset:-1840
	global_load_dword v203, v210, s[28:29] offset:-1832
	global_load_dword v204, v210, s[28:29] offset:-1824
	global_load_dword v205, v210, s[28:29] offset:-1816
	global_load_dword v206, v210, s[28:29] offset:-1808
	global_load_dword v207, v210, s[28:29] offset:-1800
	s_waitcnt vmcnt(0)
.Lp0_wout_mul:
	v_mul_f32_e32 v112, v176, v112
	ds_write_b32 v68, v112
	v_mul_f32_e32 v113, v177, v113
	ds_write_b32 v68, v113 offset:264
	v_mul_f32_e32 v114, v178, v114
	ds_write_b32 v68, v114 offset:528
	v_mul_f32_e32 v115, v179, v115
	ds_write_b32 v68, v115 offset:792
	v_mul_f32_e32 v116, v180, v116
	ds_write_b32 v68, v116 offset:1056
	v_mul_f32_e32 v117, v181, v117
	ds_write_b32 v68, v117 offset:1320
	v_mul_f32_e32 v118, v182, v118
	ds_write_b32 v68, v118 offset:1584
	v_mul_f32_e32 v119, v183, v119
	ds_write_b32 v68, v119 offset:1848
	v_mul_f32_e32 v120, v184, v120
	ds_write_b32 v68, v120 offset:2112
	v_mul_f32_e32 v121, v185, v121
	ds_write_b32 v68, v121 offset:2376
	v_mul_f32_e32 v122, v186, v122
	ds_write_b32 v68, v122 offset:2640
	v_mul_f32_e32 v123, v187, v123
	ds_write_b32 v68, v123 offset:2904
	v_mul_f32_e32 v124, v188, v124
	ds_write_b32 v68, v124 offset:3168
	v_mul_f32_e32 v125, v189, v125
	ds_write_b32 v68, v125 offset:3432
	v_mul_f32_e32 v126, v190, v126
	ds_write_b32 v68, v126 offset:3696
	v_mul_f32_e32 v127, v191, v127
	ds_write_b32 v68, v127 offset:3960
	v_mul_f32_e32 v128, v192, v128
	ds_write_b32 v68, v128 offset:4224
	v_mul_f32_e32 v129, v193, v129
	ds_write_b32 v68, v129 offset:4488
	v_mul_f32_e32 v130, v194, v130
	ds_write_b32 v68, v130 offset:4752
	v_mul_f32_e32 v131, v195, v131
	ds_write_b32 v68, v131 offset:5016
	v_mul_f32_e32 v132, v196, v132
	ds_write_b32 v68, v132 offset:5280
	v_mul_f32_e32 v133, v197, v133
	ds_write_b32 v68, v133 offset:5544
	v_mul_f32_e32 v134, v198, v134
	ds_write_b32 v68, v134 offset:5808
	v_mul_f32_e32 v135, v199, v135
	ds_write_b32 v68, v135 offset:6072
	v_mul_f32_e32 v136, v200, v136
	ds_write_b32 v68, v136 offset:6336
	v_mul_f32_e32 v137, v201, v137
	ds_write_b32 v68, v137 offset:6600
	v_mul_f32_e32 v138, v202, v138
	ds_write_b32 v68, v138 offset:6864
	v_mul_f32_e32 v139, v203, v139
	ds_write_b32 v68, v139 offset:7128
	v_mul_f32_e32 v140, v204, v140
	ds_write_b32 v68, v140 offset:7392
	v_mul_f32_e32 v141, v205, v141
	ds_write_b32 v68, v141 offset:7656
	v_mul_f32_e32 v142, v206, v142
	ds_write_b32 v68, v142 offset:7920
	v_mul_f32_e32 v143, v207, v143
	ds_write_b32 v68, v143 offset:8184
	s_branch .LBB0_93

.LBB0_106:
	v_mad_i64_i32 v[208:209], s[98:99], v30, s37, v[28:29]
	v_lshlrev_b32_e32 v210, 2, v30
	v_mov_b32_e32 v212, 0x6000
	v_mov_b32_e32 v213, 0
	global_load_dword v112, v[208:209], off
	v_lshl_add_u64 v[208:209], v[208:209], 0, v[212:213]
	global_load_dword v113, v[208:209], off
	v_lshl_add_u64 v[208:209], v[208:209], 0, v[212:213]
	global_load_dword v114, v[208:209], off
	v_lshl_add_u64 v[208:209], v[208:209], 0, v[212:213]
	global_load_dword v115, v[208:209], off
	v_lshl_add_u64 v[208:209], v[208:209], 0, v[212:213]
	global_load_dword v116, v[208:209], off
	v_lshl_add_u64 v[208:209], v[208:209], 0, v[212:213]
	global_load_dword v117, v[208:209], off
	v_lshl_add_u64 v[208:209], v[208:209], 0, v[212:213]
	global_load_dword v118, v[208:209], off
	v_lshl_add_u64 v[208:209], v[208:209], 0, v[212:213]
	global_load_dword v119, v[208:209], off
	v_lshl_add_u64 v[208:209], v[208:209], 0, v[212:213]
	global_load_dword v120, v[208:209], off
	v_lshl_add_u64 v[208:209], v[208:209], 0, v[212:213]
	global_load_dword v121, v[208:209], off
	v_lshl_add_u64 v[208:209], v[208:209], 0, v[212:213]
	global_load_dword v122, v[208:209], off
	v_lshl_add_u64 v[208:209], v[208:209], 0, v[212:213]
	global_load_dword v123, v[208:209], off
	v_lshl_add_u64 v[208:209], v[208:209], 0, v[212:213]
	global_load_dword v124, v[208:209], off
	v_lshl_add_u64 v[208:209], v[208:209], 0, v[212:213]
	global_load_dword v125, v[208:209], off
	v_lshl_add_u64 v[208:209], v[208:209], 0, v[212:213]
	global_load_dword v126, v[208:209], off
	v_lshl_add_u64 v[208:209], v[208:209], 0, v[212:213]
	global_load_dword v127, v[208:209], off
	v_lshl_add_u64 v[208:209], v[208:209], 0, v[212:213]
	global_load_dword v128, v[208:209], off
	v_lshl_add_u64 v[208:209], v[208:209], 0, v[212:213]
	global_load_dword v129, v[208:209], off
	v_lshl_add_u64 v[208:209], v[208:209], 0, v[212:213]
	global_load_dword v130, v[208:209], off
	v_lshl_add_u64 v[208:209], v[208:209], 0, v[212:213]
	global_load_dword v131, v[208:209], off
	v_lshl_add_u64 v[208:209], v[208:209], 0, v[212:213]
	global_load_dword v132, v[208:209], off
	v_lshl_add_u64 v[208:209], v[208:209], 0, v[212:213]
	global_load_dword v133, v[208:209], off
	v_lshl_add_u64 v[208:209], v[208:209], 0, v[212:213]
	global_load_dword v134, v[208:209], off
	v_lshl_add_u64 v[208:209], v[208:209], 0, v[212:213]
	global_load_dword v135, v[208:209], off
	v_lshl_add_u64 v[208:209], v[208:209], 0, v[212:213]
	global_load_dword v136, v[208:209], off
	v_lshl_add_u64 v[208:209], v[208:209], 0, v[212:213]
	global_load_dword v137, v[208:209], off
	v_lshl_add_u64 v[208:209], v[208:209], 0, v[212:213]
	global_load_dword v138, v[208:209], off
	v_lshl_add_u64 v[208:209], v[208:209], 0, v[212:213]
	global_load_dword v139, v[208:209], off
	v_lshl_add_u64 v[208:209], v[208:209], 0, v[212:213]
	global_load_dword v140, v[208:209], off
	v_lshl_add_u64 v[208:209], v[208:209], 0, v[212:213]
	global_load_dword v141, v[208:209], off
	v_lshl_add_u64 v[208:209], v[208:209], 0, v[212:213]
	global_load_dword v142, v[208:209], off
	v_lshl_add_u64 v[208:209], v[208:209], 0, v[212:213]
	global_load_dword v143, v[208:209], off
	global_load_dword v176, v210, s[20:21]
	global_load_dword v177, v210, s[20:21] offset:8
	global_load_dword v178, v210, s[20:21] offset:16
	global_load_dword v179, v210, s[20:21] offset:24
	global_load_dword v180, v210, s[20:21] offset:32
	global_load_dword v181, v210, s[20:21] offset:40
	global_load_dword v182, v210, s[20:21] offset:48
	global_load_dword v183, v210, s[20:21] offset:56
	global_load_dword v184, v210, s[20:21] offset:64
	global_load_dword v185, v210, s[20:21] offset:72
	global_load_dword v186, v210, s[20:21] offset:80
	global_load_dword v187, v210, s[20:21] offset:88
	global_load_dword v188, v210, s[20:21] offset:96
	global_load_dword v189, v210, s[20:21] offset:104
	global_load_dword v190, v210, s[20:21] offset:112
	global_load_dword v191, v210, s[20:21] offset:120
	global_load_dword v192, v210, s[20:21] offset:128
	global_load_dword v193, v210, s[20:21] offset:136
	global_load_dword v194, v210, s[20:21] offset:144
	global_load_dword v195, v210, s[20:21] offset:152
	global_load_dword v196, v210, s[20:21] offset:160
	global_load_dword v197, v210, s[20:21] offset:168
	global_load_dword v198, v210, s[20:21] offset:176
	global_load_dword v199, v210, s[20:21] offset:184
	global_load_dword v200, v210, s[20:21] offset:192
	global_load_dword v201, v210, s[20:21] offset:200
	global_load_dword v202, v210, s[20:21] offset:208
	global_load_dword v203, v210, s[20:21] offset:216
	global_load_dword v204, v210, s[20:21] offset:224
	global_load_dword v205, v210, s[20:21] offset:232
	global_load_dword v206, v210, s[20:21] offset:240
	global_load_dword v207, v210, s[20:21] offset:248
	s_waitcnt vmcnt(0)
	v_mul_f32_e32 v112, v176, v112
	ds_write_b32 v4, v112
	v_mul_f32_e32 v113, v177, v113
	ds_write_b32 v4, v113 offset:264
	v_mul_f32_e32 v114, v178, v114
	ds_write_b32 v4, v114 offset:528
	v_mul_f32_e32 v115, v179, v115
	ds_write_b32 v4, v115 offset:792
	v_mul_f32_e32 v116, v180, v116
	ds_write_b32 v4, v116 offset:1056
	v_mul_f32_e32 v117, v181, v117
	ds_write_b32 v4, v117 offset:1320
	v_mul_f32_e32 v118, v182, v118
	ds_write_b32 v4, v118 offset:1584
	v_mul_f32_e32 v119, v183, v119
	ds_write_b32 v4, v119 offset:1848
	v_mul_f32_e32 v120, v184, v120
	ds_write_b32 v4, v120 offset:2112
	v_mul_f32_e32 v121, v185, v121
	ds_write_b32 v4, v121 offset:2376
	v_mul_f32_e32 v122, v186, v122
	ds_write_b32 v4, v122 offset:2640
	v_mul_f32_e32 v123, v187, v123
	ds_write_b32 v4, v123 offset:2904
	v_mul_f32_e32 v124, v188, v124
	ds_write_b32 v4, v124 offset:3168
	v_mul_f32_e32 v125, v189, v125
	ds_write_b32 v4, v125 offset:3432
	v_mul_f32_e32 v126, v190, v126
	ds_write_b32 v4, v126 offset:3696
	v_mul_f32_e32 v127, v191, v127
	ds_write_b32 v4, v127 offset:3960
	v_mul_f32_e32 v128, v192, v128
	ds_write_b32 v4, v128 offset:4224
	v_mul_f32_e32 v129, v193, v129
	ds_write_b32 v4, v129 offset:4488
	v_mul_f32_e32 v130, v194, v130
	ds_write_b32 v4, v130 offset:4752
	v_mul_f32_e32 v131, v195, v131
	ds_write_b32 v4, v131 offset:5016
	v_mul_f32_e32 v132, v196, v132
	ds_write_b32 v4, v132 offset:5280
	v_mul_f32_e32 v133, v197, v133
	ds_write_b32 v4, v133 offset:5544
	v_mul_f32_e32 v134, v198, v134
	ds_write_b32 v4, v134 offset:5808
	v_mul_f32_e32 v135, v199, v135
	ds_write_b32 v4, v135 offset:6072
	v_mul_f32_e32 v136, v200, v136
	ds_write_b32 v4, v136 offset:6336
	v_mul_f32_e32 v137, v201, v137
	ds_write_b32 v4, v137 offset:6600
	v_mul_f32_e32 v138, v202, v138
	ds_write_b32 v4, v138 offset:6864
	v_mul_f32_e32 v139, v203, v139
	ds_write_b32 v4, v139 offset:7128
	v_mul_f32_e32 v140, v204, v140
	ds_write_b32 v4, v140 offset:7392
	v_mul_f32_e32 v141, v205, v141
	ds_write_b32 v4, v141 offset:7656
	v_mul_f32_e32 v142, v206, v142
	ds_write_b32 v4, v142 offset:7920
	v_mul_f32_e32 v143, v207, v143
	ds_write_b32 v4, v143 offset:8184
	s_branch .LBB0_13
